# P4 output-projection epilogue: residual/LN-parameter loads de-serialised (4-deep prefetch ring with counted vmcnt instead of load+wait per 16-byte group)
# speedup vs baseline: 1.0142x; 1.0008x over previous
;     __device__ __forceinline__ void operator()(const f32x4 (&acc)[2][2][4][2], const Unit& u, int wr, int wc, int fr, int fq) const {
;         const int row0 = u.pm * BM + wr * 64 + fr, col0 = u.pn * BM + wc * 32 + 4 * fq;
; #pragma unroll
;         for (int ai = 0; ai < 2; ++ai)
; #pragma unroll
;             for (int m = 0; m < 4; ++m) { const int r = row0 + ai * HALF + m * 16; const size_t off = (size_t)r * DM + col0;
;                 const float mu = stat[2 * r], rs = stat[2 * r + 1];
; #pragma unroll
;                 for (int bj = 0; bj < 2; ++bj)
; #pragma unroll
;                     for (int n = 0; n < 2; ++n) { const int c = bj * HALF + n * 16; const f32x4 y = *(const f32x4*)(Yin + off + c);
;                         const f32x4 gg = *(const f32x4*)(g + col0 + c), bb = *(const f32x4*)(b + col0 + c);
;                         const f32x4 x = (y - mu) * rs * gg + bb;
;                         *(f32x4*)(Yout + off + c) = x * ALPHA + acc[ai][bj][m][n]; }
;                 asm volatile("" ::: "memory"); }
.LBB0_806:
	v_lshl_add_u32 v146, s48, 8, v148
	v_lshl_or_b32 v144, s25, 8, v150
	v_ashrrev_i32_e32 v147, 31, v146
	v_lshlrev_b32_e32 v142, 1, v146
	v_ashrrev_i32_e32 v145, 31, v144
	v_lshlrev_b64 v[140:141], 10, v[146:147]
	v_ashrrev_i32_e32 v143, 31, v142
	v_lshl_add_u64 v[140:141], v[140:141], 0, v[144:145]
	v_lshl_add_u64 v[142:143], v[142:143], 2, s[42:43]
	v_readlane_b32 s12, v248, 1
	v_mov_b32_e32 v182, v142
	v_mov_b32_e32 v183, v143
	v_lshlrev_b64 v[166:167], 2, v[140:141]
	v_lshlrev_b64 v[142:143], 2, v[144:145]
	v_readlane_b32 s13, v248, 2
	v_lshl_add_u64 v[168:169], s[0:1], 0, v[166:167]
	v_lshl_add_u64 v[140:141], s[12:13], 0, v[142:143]
	v_readlane_b32 s12, v248, 3
	v_readlane_b32 s13, v248, 4
	v_lshl_add_u64 v[166:167], s[40:41], 0, v[166:167]
	v_lshl_add_u64 v[142:143], s[12:13], 0, v[142:143]
	s_and_b64 vcc, exec, s[36:37]
	s_mov_b64 s[36:37], -1
	v_mov_b32_e32 v178, v168
	v_mov_b32_e32 v179, v169
	s_mov_b32 s14, 0x10000
	s_mov_b32 s15, 0
	s_mov_b32 s16, 0x50000
	s_mov_b32 s17, 0
	global_load_dwordx2 v[198:199], v[182:183], off
	global_load_dwordx4 v[186:189], v[178:179], off
	global_load_dwordx4 v[190:193], v[140:141], off
	global_load_dwordx4 v[194:197], v[142:143], off
	global_load_dwordx4 v[210:213], v[178:179], off offset:64
	global_load_dwordx4 v[214:217], v[140:141], off offset:64
	global_load_dwordx4 v[218:221], v[142:143], off offset:64
	global_load_dwordx4 v[224:227], v[178:179], off offset:512
	global_load_dwordx4 v[228:231], v[140:141], off offset:512
	global_load_dwordx4 v[232:235], v[142:143], off offset:512
	global_load_dwordx4 v[238:241], v[178:179], off offset:576
	global_load_dwordx4 v[242:245], v[140:141], off offset:576
	global_load_dwordx4 v[252:255], v[142:143], off offset:576
	v_lshl_add_u64 v[178:179], v[178:179], 0, s[14:15]
	s_waitcnt vmcnt(9)
	v_mov_b32_e32 v156, v190
	v_mov_b32_e32 v157, v191
	v_mov_b32_e32 v158, v192
	v_mov_b32_e32 v159, v193
	v_mov_b32_e32 v160, v194
	v_mov_b32_e32 v161, v195
	v_mov_b32_e32 v162, v196
	v_mov_b32_e32 v163, v197
	v_mov_b32_e32 v164, v198
	v_mov_b32_e32 v165, v199
	v_mov_b32_e32 v152, v186
	v_mov_b32_e32 v153, v187
	v_mov_b32_e32 v154, v188
	v_mov_b32_e32 v155, v189
	global_load_dwordx2 v[198:199], v[182:183], off offset:128
	global_load_dwordx4 v[186:189], v[178:179], off
	global_load_dwordx4 v[190:193], v[140:141], off
	global_load_dwordx4 v[194:197], v[142:143], off
	v_sub_f32_e32 v153, v153, v164
	v_sub_f32_e32 v152, v152, v164
	v_sub_f32_e32 v155, v155, v164
	v_sub_f32_e32 v154, v154, v164
	v_pk_mul_f32 v[154:155], v[164:165], v[154:155] op_sel:[1,0]
	v_pk_mul_f32 v[152:153], v[164:165], v[152:153] op_sel:[1,0]
	v_pk_fma_f32 v[154:155], v[158:159], v[154:155], v[162:163]
	v_pk_fma_f32 v[152:153], v[156:157], v[152:153], v[160:161]
	v_pk_fma_f32 v[128:129], v[154:155], s[62:63], v[128:129] op_sel_hi:[1,0,1]
	v_pk_fma_f32 v[126:127], v[152:153], s[62:63], v[126:127] op_sel_hi:[1,0,1]
	global_store_dwordx4 v[166:167], v[126:129], off
	s_nop 0
	s_waitcnt vmcnt(11)
	v_mov_b32_e32 v152, v214
	v_mov_b32_e32 v153, v215
	v_mov_b32_e32 v154, v216
	v_mov_b32_e32 v155, v217
	v_mov_b32_e32 v156, v218
	v_mov_b32_e32 v157, v219
	v_mov_b32_e32 v158, v220
	v_mov_b32_e32 v159, v221
	v_mov_b32_e32 v126, v210
	v_mov_b32_e32 v127, v211
	v_mov_b32_e32 v128, v212
	v_mov_b32_e32 v129, v213
	global_load_dwordx4 v[210:213], v[178:179], off offset:64
	global_load_dwordx4 v[214:217], v[140:141], off offset:64
	global_load_dwordx4 v[218:221], v[142:143], off offset:64
	v_sub_f32_e32 v127, v127, v164
	v_sub_f32_e32 v126, v126, v164
	v_sub_f32_e32 v129, v129, v164
	v_sub_f32_e32 v128, v128, v164
	v_pk_mul_f32 v[128:129], v[164:165], v[128:129] op_sel:[1,0]
	v_pk_mul_f32 v[126:127], v[164:165], v[126:127] op_sel:[1,0]
	v_pk_fma_f32 v[128:129], v[154:155], v[128:129], v[158:159]
	v_pk_fma_f32 v[126:127], v[152:153], v[126:127], v[156:157]
	v_pk_fma_f32 v[124:125], v[128:129], s[62:63], v[124:125] op_sel_hi:[1,0,1]
	v_pk_fma_f32 v[122:123], v[126:127], s[62:63], v[122:123] op_sel_hi:[1,0,1]
	global_store_dwordx4 v[166:167], v[122:125], off offset:64
	s_nop 0
	s_waitcnt vmcnt(12)
	v_mov_b32_e32 v126, v228
	v_mov_b32_e32 v127, v229
	v_mov_b32_e32 v128, v230
	v_mov_b32_e32 v129, v231
	v_mov_b32_e32 v152, v232
	v_mov_b32_e32 v153, v233
	v_mov_b32_e32 v154, v234
	v_mov_b32_e32 v155, v235
	v_mov_b32_e32 v122, v224
	v_mov_b32_e32 v123, v225
	v_mov_b32_e32 v124, v226
	v_mov_b32_e32 v125, v227
	global_load_dwordx4 v[224:227], v[178:179], off offset:512
	global_load_dwordx4 v[228:231], v[140:141], off offset:512
	global_load_dwordx4 v[232:235], v[142:143], off offset:512
	v_sub_f32_e32 v123, v123, v164
	v_sub_f32_e32 v122, v122, v164
	v_sub_f32_e32 v125, v125, v164
	v_sub_f32_e32 v124, v124, v164
	v_pk_mul_f32 v[124:125], v[164:165], v[124:125] op_sel:[1,0]
	v_pk_mul_f32 v[122:123], v[164:165], v[122:123] op_sel:[1,0]
	v_pk_fma_f32 v[124:125], v[128:129], v[124:125], v[154:155]
	v_pk_fma_f32 v[122:123], v[126:127], v[122:123], v[152:153]
	v_pk_fma_f32 v[120:121], v[124:125], s[62:63], v[120:121] op_sel_hi:[1,0,1]
	v_pk_fma_f32 v[118:119], v[122:123], s[62:63], v[118:119] op_sel_hi:[1,0,1]
	global_store_dwordx4 v[166:167], v[118:121], off offset:512
	s_nop 0
	v_or_b32_e32 v152, 16, v146
	v_ashrrev_i32_e32 v153, 31, v152
	v_lshlrev_b32_e32 v154, 1, v152
	v_lshlrev_b64 v[152:153], 10, v[152:153]
	v_ashrrev_i32_e32 v155, 31, v154
	v_lshl_add_u64 v[152:153], v[152:153], 0, v[144:145]
	v_lshl_add_u64 v[154:155], v[154:155], 2, s[42:43]
	v_lshlrev_b64 v[152:153], 2, v[152:153]
	v_lshl_add_u64 v[156:157], s[0:1], 0, v[152:153]
	s_waitcnt vmcnt(13)
;     __device__ __forceinline__ void operator()(const f32x4 (&acc)[2][2][4][2], const Unit& u, int wr, int wc, int fr, int fq) const {
;         const int row0 = u.pm * BM + wr * 64 + fr, col0 = u.pn * BM + wc * 32 + 4 * fq;
; #pragma unroll
;         for (int ai = 0; ai < 2; ++ai)
; #pragma unroll
;             for (int m = 0; m < 4; ++m) { const int r = row0 + ai * HALF + m * 16; const size_t off = (size_t)r * DM + col0;
;                 const float mu = stat[2 * r], rs = stat[2 * r + 1];
; #pragma unroll
;                 for (int bj = 0; bj < 2; ++bj)
; #pragma unroll
;                     for (int n = 0; n < 2; ++n) { const int c = bj * HALF + n * 16; const f32x4 y = *(const f32x4*)(Yin + off + c);
;                         const f32x4 gg = *(const f32x4*)(g + col0 + c), bb = *(const f32x4*)(b + col0 + c);
;                         const f32x4 x = (y - mu) * rs * gg + bb;
;                         *(f32x4*)(Yout + off + c) = x * ALPHA + acc[ai][bj][m][n]; }
;                 asm volatile("" ::: "memory"); }
	v_mov_b32_e32 v122, v242
	v_mov_b32_e32 v123, v243
	v_mov_b32_e32 v124, v244
	v_mov_b32_e32 v125, v245
	v_mov_b32_e32 v126, v252
	v_mov_b32_e32 v127, v253
	v_mov_b32_e32 v128, v254
	v_mov_b32_e32 v129, v255
	v_mov_b32_e32 v118, v238
	v_mov_b32_e32 v119, v239
	v_mov_b32_e32 v120, v240
	v_mov_b32_e32 v121, v241
	global_load_dwordx4 v[238:241], v[178:179], off offset:576
	global_load_dwordx4 v[242:245], v[140:141], off offset:576
	global_load_dwordx4 v[252:255], v[142:143], off offset:576
	v_lshl_add_u64 v[178:179], v[178:179], 0, s[14:15]
	v_sub_f32_e32 v119, v119, v164
	v_sub_f32_e32 v118, v118, v164
	v_sub_f32_e32 v121, v121, v164
	v_sub_f32_e32 v120, v120, v164
	v_pk_mul_f32 v[120:121], v[164:165], v[120:121] op_sel:[1,0]
	v_pk_mul_f32 v[118:119], v[164:165], v[118:119] op_sel:[1,0]
	v_pk_fma_f32 v[120:121], v[124:125], v[120:121], v[128:129]
	v_pk_fma_f32 v[118:119], v[122:123], v[118:119], v[126:127]
	v_pk_fma_f32 v[116:117], v[120:121], s[62:63], v[116:117] op_sel_hi:[1,0,1]
	v_pk_fma_f32 v[114:115], v[118:119], s[62:63], v[114:115] op_sel_hi:[1,0,1]
	global_store_dwordx4 v[166:167], v[114:117], off offset:576
	v_lshl_add_u64 v[128:129], s[40:41], 0, v[152:153]
	s_waitcnt vmcnt(13)
	v_mov_b32_e32 v118, v190
	v_mov_b32_e32 v119, v191
	v_mov_b32_e32 v120, v192
	v_mov_b32_e32 v121, v193
	v_mov_b32_e32 v122, v194
	v_mov_b32_e32 v123, v195
	v_mov_b32_e32 v124, v196
	v_mov_b32_e32 v125, v197
	v_mov_b32_e32 v126, v198
	v_mov_b32_e32 v127, v199
	v_mov_b32_e32 v114, v186
	v_mov_b32_e32 v115, v187
	v_mov_b32_e32 v116, v188
	v_mov_b32_e32 v117, v189
	global_load_dwordx2 v[198:199], v[182:183], off offset:256
	global_load_dwordx4 v[186:189], v[178:179], off
	global_load_dwordx4 v[190:193], v[140:141], off
	global_load_dwordx4 v[194:197], v[142:143], off
	v_sub_f32_e32 v115, v115, v126
	v_sub_f32_e32 v114, v114, v126
	v_sub_f32_e32 v117, v117, v126
	v_sub_f32_e32 v116, v116, v126
	v_pk_mul_f32 v[116:117], v[126:127], v[116:117] op_sel:[1,0]
	v_pk_mul_f32 v[114:115], v[126:127], v[114:115] op_sel:[1,0]
	v_pk_fma_f32 v[116:117], v[120:121], v[116:117], v[124:125]
	v_pk_fma_f32 v[114:115], v[118:119], v[114:115], v[122:123]
	v_pk_fma_f32 v[112:113], v[116:117], s[62:63], v[112:113] op_sel_hi:[1,0,1]
	v_pk_fma_f32 v[110:111], v[114:115], s[62:63], v[110:111] op_sel_hi:[1,0,1]
	global_store_dwordx4 v[128:129], v[110:113], off
	s_nop 0
	s_waitcnt vmcnt(14)
	v_mov_b32_e32 v114, v214
	v_mov_b32_e32 v115, v215
	v_mov_b32_e32 v116, v216
	v_mov_b32_e32 v117, v217
	v_mov_b32_e32 v118, v218
	v_mov_b32_e32 v119, v219
	v_mov_b32_e32 v120, v220
	v_mov_b32_e32 v121, v221
	v_mov_b32_e32 v110, v210
	v_mov_b32_e32 v111, v211
	v_mov_b32_e32 v112, v212
	v_mov_b32_e32 v113, v213
	global_load_dwordx4 v[210:213], v[178:179], off offset:64
	global_load_dwordx4 v[214:217], v[140:141], off offset:64
	global_load_dwordx4 v[218:221], v[142:143], off offset:64
	v_sub_f32_e32 v111, v111, v126
	v_sub_f32_e32 v110, v110, v126
	v_sub_f32_e32 v113, v113, v126
	v_sub_f32_e32 v112, v112, v126
	v_pk_mul_f32 v[112:113], v[126:127], v[112:113] op_sel:[1,0]
	v_pk_mul_f32 v[110:111], v[126:127], v[110:111] op_sel:[1,0]
	v_pk_fma_f32 v[112:113], v[116:117], v[112:113], v[120:121]
	v_pk_fma_f32 v[110:111], v[114:115], v[110:111], v[118:119]
	v_pk_fma_f32 v[108:109], v[112:113], s[62:63], v[108:109] op_sel_hi:[1,0,1]
	v_pk_fma_f32 v[106:107], v[110:111], s[62:63], v[106:107] op_sel_hi:[1,0,1]
	global_store_dwordx4 v[128:129], v[106:109], off offset:64
	s_nop 0
	s_waitcnt vmcnt(14)
	v_mov_b32_e32 v110, v228
	v_mov_b32_e32 v111, v229
	v_mov_b32_e32 v112, v230
	v_mov_b32_e32 v113, v231
	v_mov_b32_e32 v114, v232
	v_mov_b32_e32 v115, v233
	v_mov_b32_e32 v116, v234
	v_mov_b32_e32 v117, v235
	v_mov_b32_e32 v106, v224
	v_mov_b32_e32 v107, v225
	v_mov_b32_e32 v108, v226
	v_mov_b32_e32 v109, v227
	global_load_dwordx4 v[224:227], v[178:179], off offset:512
	global_load_dwordx4 v[228:231], v[140:141], off offset:512
	global_load_dwordx4 v[232:235], v[142:143], off offset:512
	v_sub_f32_e32 v107, v107, v126
	v_sub_f32_e32 v106, v106, v126
	v_sub_f32_e32 v109, v109, v126
	v_sub_f32_e32 v108, v108, v126
	v_pk_mul_f32 v[108:109], v[126:127], v[108:109] op_sel:[1,0]
	v_pk_mul_f32 v[106:107], v[126:127], v[106:107] op_sel:[1,0]
	v_pk_fma_f32 v[108:109], v[112:113], v[108:109], v[116:117]
	v_pk_fma_f32 v[106:107], v[110:111], v[106:107], v[114:115]
	v_pk_fma_f32 v[104:105], v[108:109], s[62:63], v[104:105] op_sel_hi:[1,0,1]
	v_pk_fma_f32 v[102:103], v[106:107], s[62:63], v[102:103] op_sel_hi:[1,0,1]
	global_store_dwordx4 v[128:129], v[102:105], off offset:512
	s_nop 0
	v_or_b32_e32 v114, 32, v146
	v_ashrrev_i32_e32 v115, 31, v114
	v_lshlrev_b32_e32 v116, 1, v114
	v_lshlrev_b64 v[114:115], 10, v[114:115]
	v_ashrrev_i32_e32 v117, 31, v116
	v_lshl_add_u64 v[114:115], v[114:115], 0, v[144:145]
	v_lshl_add_u64 v[116:117], v[116:117], 2, s[42:43]
	v_lshlrev_b64 v[114:115], 2, v[114:115]
	v_lshl_add_u64 v[118:119], s[0:1], 0, v[114:115]
	s_waitcnt vmcnt(14)
	v_mov_b32_e32 v106, v242
	v_mov_b32_e32 v107, v243
	v_mov_b32_e32 v108, v244
	v_mov_b32_e32 v109, v245
	v_mov_b32_e32 v110, v252
	v_mov_b32_e32 v111, v253
	v_mov_b32_e32 v112, v254
	v_mov_b32_e32 v113, v255
	v_mov_b32_e32 v102, v238
	v_mov_b32_e32 v103, v239
	v_mov_b32_e32 v104, v240
	v_mov_b32_e32 v105, v241
	global_load_dwordx4 v[238:241], v[178:179], off offset:576
	global_load_dwordx4 v[242:245], v[140:141], off offset:576
	global_load_dwordx4 v[252:255], v[142:143], off offset:576
	v_lshl_add_u64 v[178:179], v[178:179], 0, s[14:15]
	v_sub_f32_e32 v103, v103, v126
	v_sub_f32_e32 v102, v102, v126
	v_sub_f32_e32 v105, v105, v126
	v_sub_f32_e32 v104, v104, v126
	v_pk_mul_f32 v[104:105], v[126:127], v[104:105] op_sel:[1,0]
	v_pk_mul_f32 v[102:103], v[126:127], v[102:103] op_sel:[1,0]
	v_pk_fma_f32 v[104:105], v[108:109], v[104:105], v[112:113]
	v_pk_fma_f32 v[102:103], v[106:107], v[102:103], v[110:111]
	v_pk_fma_f32 v[100:101], v[104:105], s[62:63], v[100:101] op_sel_hi:[1,0,1]
	v_pk_fma_f32 v[98:99], v[102:103], s[62:63], v[98:99] op_sel_hi:[1,0,1]
	global_store_dwordx4 v[128:129], v[98:101], off offset:576
	v_lshl_add_u64 v[112:113], s[40:41], 0, v[114:115]
	s_waitcnt vmcnt(13)
;     __device__ __forceinline__ void operator()(const f32x4 (&acc)[2][2][4][2], const Unit& u, int wr, int wc, int fr, int fq) const {
;         const int row0 = u.pm * BM + wr * 64 + fr, col0 = u.pn * BM + wc * 32 + 4 * fq;
; #pragma unroll
;         for (int ai = 0; ai < 2; ++ai)
; #pragma unroll
;             for (int m = 0; m < 4; ++m) { const int r = row0 + ai * HALF + m * 16; const size_t off = (size_t)r * DM + col0;
;                 const float mu = stat[2 * r], rs = stat[2 * r + 1];
; #pragma unroll
;                 for (int bj = 0; bj < 2; ++bj)
; #pragma unroll
;                     for (int n = 0; n < 2; ++n) { const int c = bj * HALF + n * 16; const f32x4 y = *(const f32x4*)(Yin + off + c);
;                         const f32x4 gg = *(const f32x4*)(g + col0 + c), bb = *(const f32x4*)(b + col0 + c);
;                         const f32x4 x = (y - mu) * rs * gg + bb;
;                         *(f32x4*)(Yout + off + c) = x * ALPHA + acc[ai][bj][m][n]; }
;                 asm volatile("" ::: "memory"); }
	v_mov_b32_e32 v102, v190
	v_mov_b32_e32 v103, v191
	v_mov_b32_e32 v104, v192
	v_mov_b32_e32 v105, v193
	v_mov_b32_e32 v106, v194
	v_mov_b32_e32 v107, v195
	v_mov_b32_e32 v108, v196
	v_mov_b32_e32 v109, v197
	v_mov_b32_e32 v110, v198
	v_mov_b32_e32 v111, v199
	v_mov_b32_e32 v98, v186
	v_mov_b32_e32 v99, v187
	v_mov_b32_e32 v100, v188
	v_mov_b32_e32 v101, v189
	global_load_dwordx2 v[198:199], v[182:183], off offset:384
	global_load_dwordx4 v[186:189], v[178:179], off
	global_load_dwordx4 v[190:193], v[140:141], off
	global_load_dwordx4 v[194:197], v[142:143], off
	v_sub_f32_e32 v99, v99, v110
	v_sub_f32_e32 v98, v98, v110
	v_sub_f32_e32 v101, v101, v110
	v_sub_f32_e32 v100, v100, v110
	v_pk_mul_f32 v[100:101], v[110:111], v[100:101] op_sel:[1,0]
	v_pk_mul_f32 v[98:99], v[110:111], v[98:99] op_sel:[1,0]
	v_pk_fma_f32 v[100:101], v[104:105], v[100:101], v[108:109]
	v_pk_fma_f32 v[98:99], v[102:103], v[98:99], v[106:107]
	v_pk_fma_f32 v[94:95], v[100:101], s[62:63], v[94:95] op_sel_hi:[1,0,1]
	v_pk_fma_f32 v[92:93], v[98:99], s[62:63], v[92:93] op_sel_hi:[1,0,1]
	global_store_dwordx4 v[112:113], v[92:95], off
	s_nop 0
	s_waitcnt vmcnt(14)
	v_mov_b32_e32 v98, v214
	v_mov_b32_e32 v99, v215
	v_mov_b32_e32 v100, v216
	v_mov_b32_e32 v101, v217
	v_mov_b32_e32 v102, v218
	v_mov_b32_e32 v103, v219
	v_mov_b32_e32 v104, v220
	v_mov_b32_e32 v105, v221
	v_mov_b32_e32 v92, v210
	v_mov_b32_e32 v93, v211
	v_mov_b32_e32 v94, v212
	v_mov_b32_e32 v95, v213
	global_load_dwordx4 v[210:213], v[178:179], off offset:64
	global_load_dwordx4 v[214:217], v[140:141], off offset:64
	global_load_dwordx4 v[218:221], v[142:143], off offset:64
	v_sub_f32_e32 v93, v93, v110
	v_sub_f32_e32 v92, v92, v110
	v_sub_f32_e32 v95, v95, v110
	v_sub_f32_e32 v94, v94, v110
	v_pk_mul_f32 v[94:95], v[110:111], v[94:95] op_sel:[1,0]
	v_pk_mul_f32 v[92:93], v[110:111], v[92:93] op_sel:[1,0]
	v_pk_fma_f32 v[94:95], v[100:101], v[94:95], v[104:105]
	v_pk_fma_f32 v[92:93], v[98:99], v[92:93], v[102:103]
	v_pk_fma_f32 v[90:91], v[94:95], s[62:63], v[90:91] op_sel_hi:[1,0,1]
	v_pk_fma_f32 v[88:89], v[92:93], s[62:63], v[88:89] op_sel_hi:[1,0,1]
	global_store_dwordx4 v[112:113], v[88:91], off offset:64
	s_nop 0
	s_waitcnt vmcnt(14)
	v_mov_b32_e32 v92, v228
	v_mov_b32_e32 v93, v229
	v_mov_b32_e32 v94, v230
	v_mov_b32_e32 v95, v231
	v_mov_b32_e32 v98, v232
	v_mov_b32_e32 v99, v233
	v_mov_b32_e32 v100, v234
	v_mov_b32_e32 v101, v235
	v_mov_b32_e32 v88, v224
	v_mov_b32_e32 v89, v225
	v_mov_b32_e32 v90, v226
	v_mov_b32_e32 v91, v227
	global_load_dwordx4 v[224:227], v[178:179], off offset:512
	global_load_dwordx4 v[228:231], v[140:141], off offset:512
	global_load_dwordx4 v[232:235], v[142:143], off offset:512
	v_sub_f32_e32 v89, v89, v110
	v_sub_f32_e32 v88, v88, v110
	v_sub_f32_e32 v91, v91, v110
	v_sub_f32_e32 v90, v90, v110
	v_pk_mul_f32 v[90:91], v[110:111], v[90:91] op_sel:[1,0]
	v_pk_mul_f32 v[88:89], v[110:111], v[88:89] op_sel:[1,0]
	v_pk_fma_f32 v[90:91], v[94:95], v[90:91], v[100:101]
	v_pk_fma_f32 v[88:89], v[92:93], v[88:89], v[98:99]
	v_pk_fma_f32 v[86:87], v[90:91], s[62:63], v[86:87] op_sel_hi:[1,0,1]
	v_pk_fma_f32 v[84:85], v[88:89], s[62:63], v[84:85] op_sel_hi:[1,0,1]
	global_store_dwordx4 v[112:113], v[84:87], off offset:512
	s_nop 0
	v_or_b32_e32 v98, 48, v146
	v_ashrrev_i32_e32 v99, 31, v98
	v_lshlrev_b32_e32 v100, 1, v98
	v_lshlrev_b64 v[98:99], 10, v[98:99]
	v_ashrrev_i32_e32 v101, 31, v100
	v_lshl_add_u64 v[98:99], v[98:99], 0, v[144:145]
	v_lshl_add_u64 v[100:101], v[100:101], 2, s[42:43]
	v_lshlrev_b64 v[98:99], 2, v[98:99]
	v_lshl_add_u64 v[102:103], s[0:1], 0, v[98:99]
	s_waitcnt vmcnt(14)
	v_mov_b32_e32 v88, v242
	v_mov_b32_e32 v89, v243
	v_mov_b32_e32 v90, v244
	v_mov_b32_e32 v91, v245
	v_mov_b32_e32 v92, v252
	v_mov_b32_e32 v93, v253
	v_mov_b32_e32 v94, v254
	v_mov_b32_e32 v95, v255
	v_mov_b32_e32 v84, v238
	v_mov_b32_e32 v85, v239
	v_mov_b32_e32 v86, v240
	v_mov_b32_e32 v87, v241
	global_load_dwordx4 v[238:241], v[178:179], off offset:576
	global_load_dwordx4 v[242:245], v[140:141], off offset:576
	global_load_dwordx4 v[252:255], v[142:143], off offset:576
	v_lshl_add_u64 v[178:179], v[178:179], 0, s[16:17]
	v_sub_f32_e32 v85, v85, v110
	v_sub_f32_e32 v84, v84, v110
	v_sub_f32_e32 v87, v87, v110
	v_sub_f32_e32 v86, v86, v110
	v_pk_mul_f32 v[86:87], v[110:111], v[86:87] op_sel:[1,0]
	v_pk_mul_f32 v[84:85], v[110:111], v[84:85] op_sel:[1,0]
	v_pk_fma_f32 v[86:87], v[90:91], v[86:87], v[94:95]
	v_pk_fma_f32 v[84:85], v[88:89], v[84:85], v[92:93]
	v_pk_fma_f32 v[82:83], v[86:87], s[62:63], v[82:83] op_sel_hi:[1,0,1]
	v_pk_fma_f32 v[80:81], v[84:85], s[62:63], v[80:81] op_sel_hi:[1,0,1]
	global_store_dwordx4 v[112:113], v[80:83], off offset:576
	v_lshl_add_u64 v[94:95], s[40:41], 0, v[98:99]
	s_waitcnt vmcnt(13)
	v_mov_b32_e32 v84, v190
	v_mov_b32_e32 v85, v191
	v_mov_b32_e32 v86, v192
	v_mov_b32_e32 v87, v193
	v_mov_b32_e32 v88, v194
	v_mov_b32_e32 v89, v195
	v_mov_b32_e32 v90, v196
	v_mov_b32_e32 v91, v197
	v_mov_b32_e32 v92, v198
	v_mov_b32_e32 v93, v199
	v_mov_b32_e32 v80, v186
	v_mov_b32_e32 v81, v187
	v_mov_b32_e32 v82, v188
	v_mov_b32_e32 v83, v189
	global_load_dwordx2 v[198:199], v[182:183], off offset:1024
	global_load_dwordx4 v[186:189], v[178:179], off
	global_load_dwordx4 v[190:193], v[140:141], off
	global_load_dwordx4 v[194:197], v[142:143], off
	v_sub_f32_e32 v81, v81, v92
	v_sub_f32_e32 v80, v80, v92
	v_sub_f32_e32 v83, v83, v92
	v_sub_f32_e32 v82, v82, v92
	v_pk_mul_f32 v[82:83], v[92:93], v[82:83] op_sel:[1,0]
	v_pk_mul_f32 v[80:81], v[92:93], v[80:81] op_sel:[1,0]
	v_pk_fma_f32 v[82:83], v[86:87], v[82:83], v[90:91]
	v_pk_fma_f32 v[80:81], v[84:85], v[80:81], v[88:89]
	v_pk_fma_f32 v[78:79], v[82:83], s[62:63], v[78:79] op_sel_hi:[1,0,1]
	v_pk_fma_f32 v[76:77], v[80:81], s[62:63], v[76:77] op_sel_hi:[1,0,1]
	global_store_dwordx4 v[94:95], v[76:79], off
	s_nop 0
	s_waitcnt vmcnt(14)
;     __device__ __forceinline__ void operator()(const f32x4 (&acc)[2][2][4][2], const Unit& u, int wr, int wc, int fr, int fq) const {
;         const int row0 = u.pm * BM + wr * 64 + fr, col0 = u.pn * BM + wc * 32 + 4 * fq;
; #pragma unroll
;         for (int ai = 0; ai < 2; ++ai)
; #pragma unroll
;             for (int m = 0; m < 4; ++m) { const int r = row0 + ai * HALF + m * 16; const size_t off = (size_t)r * DM + col0;
;                 const float mu = stat[2 * r], rs = stat[2 * r + 1];
; #pragma unroll
;                 for (int bj = 0; bj < 2; ++bj)
; #pragma unroll
;                     for (int n = 0; n < 2; ++n) { const int c = bj * HALF + n * 16; const f32x4 y = *(const f32x4*)(Yin + off + c);
;                         const f32x4 gg = *(const f32x4*)(g + col0 + c), bb = *(const f32x4*)(b + col0 + c);
;                         const f32x4 x = (y - mu) * rs * gg + bb;
;                         *(f32x4*)(Yout + off + c) = x * ALPHA + acc[ai][bj][m][n]; }
;                 asm volatile("" ::: "memory"); }
	v_mov_b32_e32 v80, v214
	v_mov_b32_e32 v81, v215
	v_mov_b32_e32 v82, v216
	v_mov_b32_e32 v83, v217
	v_mov_b32_e32 v84, v218
	v_mov_b32_e32 v85, v219
	v_mov_b32_e32 v86, v220
	v_mov_b32_e32 v87, v221
	v_mov_b32_e32 v76, v210
	v_mov_b32_e32 v77, v211
	v_mov_b32_e32 v78, v212
	v_mov_b32_e32 v79, v213
	global_load_dwordx4 v[210:213], v[178:179], off offset:64
	global_load_dwordx4 v[214:217], v[140:141], off offset:64
	global_load_dwordx4 v[218:221], v[142:143], off offset:64
	v_sub_f32_e32 v77, v77, v92
	v_sub_f32_e32 v76, v76, v92
	v_sub_f32_e32 v79, v79, v92
	v_sub_f32_e32 v78, v78, v92
	v_pk_mul_f32 v[78:79], v[92:93], v[78:79] op_sel:[1,0]
	v_pk_mul_f32 v[76:77], v[92:93], v[76:77] op_sel:[1,0]
	v_pk_fma_f32 v[78:79], v[82:83], v[78:79], v[86:87]
	v_pk_fma_f32 v[76:77], v[80:81], v[76:77], v[84:85]
	v_pk_fma_f32 v[74:75], v[78:79], s[62:63], v[74:75] op_sel_hi:[1,0,1]
	v_pk_fma_f32 v[72:73], v[76:77], s[62:63], v[72:73] op_sel_hi:[1,0,1]
	global_store_dwordx4 v[94:95], v[72:75], off offset:64
	s_nop 0
	s_waitcnt vmcnt(14)
	v_mov_b32_e32 v76, v228
	v_mov_b32_e32 v77, v229
	v_mov_b32_e32 v78, v230
	v_mov_b32_e32 v79, v231
	v_mov_b32_e32 v80, v232
	v_mov_b32_e32 v81, v233
	v_mov_b32_e32 v82, v234
	v_mov_b32_e32 v83, v235
	v_mov_b32_e32 v72, v224
	v_mov_b32_e32 v73, v225
	v_mov_b32_e32 v74, v226
	v_mov_b32_e32 v75, v227
	global_load_dwordx4 v[224:227], v[178:179], off offset:512
	global_load_dwordx4 v[228:231], v[140:141], off offset:512
	global_load_dwordx4 v[232:235], v[142:143], off offset:512
	v_sub_f32_e32 v73, v73, v92
	v_sub_f32_e32 v72, v72, v92
	v_sub_f32_e32 v75, v75, v92
	v_sub_f32_e32 v74, v74, v92
	v_pk_mul_f32 v[74:75], v[92:93], v[74:75] op_sel:[1,0]
	v_pk_mul_f32 v[72:73], v[92:93], v[72:73] op_sel:[1,0]
	v_pk_fma_f32 v[74:75], v[78:79], v[74:75], v[82:83]
	v_pk_fma_f32 v[72:73], v[76:77], v[72:73], v[80:81]
	v_pk_fma_f32 v[70:71], v[74:75], s[62:63], v[70:71] op_sel_hi:[1,0,1]
	v_pk_fma_f32 v[68:69], v[72:73], s[62:63], v[68:69] op_sel_hi:[1,0,1]
	global_store_dwordx4 v[94:95], v[68:71], off offset:512
	s_nop 0
	v_add_u32_e32 v80, 0x80, v146
	v_ashrrev_i32_e32 v81, 31, v80
	v_lshlrev_b32_e32 v82, 1, v80
	v_lshlrev_b64 v[80:81], 10, v[80:81]
	v_ashrrev_i32_e32 v83, 31, v82
	v_lshl_add_u64 v[80:81], v[80:81], 0, v[144:145]
	v_lshl_add_u64 v[82:83], v[82:83], 2, s[42:43]
	v_lshlrev_b64 v[80:81], 2, v[80:81]
	v_lshl_add_u64 v[84:85], s[0:1], 0, v[80:81]
	s_waitcnt vmcnt(14)
	v_mov_b32_e32 v72, v242
	v_mov_b32_e32 v73, v243
	v_mov_b32_e32 v74, v244
	v_mov_b32_e32 v75, v245
	v_mov_b32_e32 v76, v252
	v_mov_b32_e32 v77, v253
	v_mov_b32_e32 v78, v254
	v_mov_b32_e32 v79, v255
	v_mov_b32_e32 v68, v238
	v_mov_b32_e32 v69, v239
	v_mov_b32_e32 v70, v240
	v_mov_b32_e32 v71, v241
	global_load_dwordx4 v[238:241], v[178:179], off offset:576
	global_load_dwordx4 v[242:245], v[140:141], off offset:576
	global_load_dwordx4 v[252:255], v[142:143], off offset:576
	v_lshl_add_u64 v[178:179], v[178:179], 0, s[14:15]
	v_sub_f32_e32 v69, v69, v92
	v_sub_f32_e32 v68, v68, v92
	v_sub_f32_e32 v71, v71, v92
	v_sub_f32_e32 v70, v70, v92
	v_pk_mul_f32 v[70:71], v[92:93], v[70:71] op_sel:[1,0]
	v_pk_mul_f32 v[68:69], v[92:93], v[68:69] op_sel:[1,0]
	v_pk_fma_f32 v[70:71], v[74:75], v[70:71], v[78:79]
	v_pk_fma_f32 v[68:69], v[72:73], v[68:69], v[76:77]
	v_pk_fma_f32 v[66:67], v[70:71], s[62:63], v[66:67] op_sel_hi:[1,0,1]
	v_pk_fma_f32 v[64:65], v[68:69], s[62:63], v[64:65] op_sel_hi:[1,0,1]
	global_store_dwordx4 v[94:95], v[64:67], off offset:576
	v_lshl_add_u64 v[78:79], s[40:41], 0, v[80:81]
	s_waitcnt vmcnt(13)
	v_mov_b32_e32 v68, v190
	v_mov_b32_e32 v69, v191
	v_mov_b32_e32 v70, v192
	v_mov_b32_e32 v71, v193
	v_mov_b32_e32 v72, v194
	v_mov_b32_e32 v73, v195
	v_mov_b32_e32 v74, v196
	v_mov_b32_e32 v75, v197
	v_mov_b32_e32 v76, v198
	v_mov_b32_e32 v77, v199
	v_mov_b32_e32 v64, v186
	v_mov_b32_e32 v65, v187
	v_mov_b32_e32 v66, v188
	v_mov_b32_e32 v67, v189
	global_load_dwordx2 v[198:199], v[182:183], off offset:1152
	global_load_dwordx4 v[186:189], v[178:179], off
	global_load_dwordx4 v[190:193], v[140:141], off
	global_load_dwordx4 v[194:197], v[142:143], off
	v_sub_f32_e32 v65, v65, v76
	v_sub_f32_e32 v64, v64, v76
	v_sub_f32_e32 v67, v67, v76
	v_sub_f32_e32 v66, v66, v76
	v_pk_mul_f32 v[66:67], v[76:77], v[66:67] op_sel:[1,0]
	v_pk_mul_f32 v[64:65], v[76:77], v[64:65] op_sel:[1,0]
	v_pk_fma_f32 v[66:67], v[70:71], v[66:67], v[74:75]
	v_pk_fma_f32 v[64:65], v[68:69], v[64:65], v[72:73]
	v_pk_fma_f32 v[62:63], v[66:67], s[62:63], v[62:63] op_sel_hi:[1,0,1]
	v_pk_fma_f32 v[60:61], v[64:65], s[62:63], v[60:61] op_sel_hi:[1,0,1]
	global_store_dwordx4 v[78:79], v[60:63], off
	s_nop 0
	s_waitcnt vmcnt(14)
	v_mov_b32_e32 v64, v214
	v_mov_b32_e32 v65, v215
	v_mov_b32_e32 v66, v216
	v_mov_b32_e32 v67, v217
	v_mov_b32_e32 v68, v218
	v_mov_b32_e32 v69, v219
	v_mov_b32_e32 v70, v220
	v_mov_b32_e32 v71, v221
	v_mov_b32_e32 v60, v210
	v_mov_b32_e32 v61, v211
	v_mov_b32_e32 v62, v212
	v_mov_b32_e32 v63, v213
	global_load_dwordx4 v[210:213], v[178:179], off offset:64
	global_load_dwordx4 v[214:217], v[140:141], off offset:64
	global_load_dwordx4 v[218:221], v[142:143], off offset:64
	v_sub_f32_e32 v61, v61, v76
	v_sub_f32_e32 v60, v60, v76
	v_sub_f32_e32 v63, v63, v76
	v_sub_f32_e32 v62, v62, v76
	v_pk_mul_f32 v[62:63], v[76:77], v[62:63] op_sel:[1,0]
	v_pk_mul_f32 v[60:61], v[76:77], v[60:61] op_sel:[1,0]
	v_pk_fma_f32 v[62:63], v[66:67], v[62:63], v[70:71]
	v_pk_fma_f32 v[60:61], v[64:65], v[60:61], v[68:69]
	v_pk_fma_f32 v[58:59], v[62:63], s[62:63], v[58:59] op_sel_hi:[1,0,1]
	v_pk_fma_f32 v[56:57], v[60:61], s[62:63], v[56:57] op_sel_hi:[1,0,1]
	global_store_dwordx4 v[78:79], v[56:59], off offset:64
	s_nop 0
	s_waitcnt vmcnt(14)
;     __device__ __forceinline__ void operator()(const f32x4 (&acc)[2][2][4][2], const Unit& u, int wr, int wc, int fr, int fq) const {
;         const int row0 = u.pm * BM + wr * 64 + fr, col0 = u.pn * BM + wc * 32 + 4 * fq;
; #pragma unroll
;         for (int ai = 0; ai < 2; ++ai)
; #pragma unroll
;             for (int m = 0; m < 4; ++m) { const int r = row0 + ai * HALF + m * 16; const size_t off = (size_t)r * DM + col0;
;                 const float mu = stat[2 * r], rs = stat[2 * r + 1];
; #pragma unroll
;                 for (int bj = 0; bj < 2; ++bj)
; #pragma unroll
;                     for (int n = 0; n < 2; ++n) { const int c = bj * HALF + n * 16; const f32x4 y = *(const f32x4*)(Yin + off + c);
;                         const f32x4 gg = *(const f32x4*)(g + col0 + c), bb = *(const f32x4*)(b + col0 + c);
;                         const f32x4 x = (y - mu) * rs * gg + bb;
;                         *(f32x4*)(Yout + off + c) = x * ALPHA + acc[ai][bj][m][n]; }
;                 asm volatile("" ::: "memory"); }
	v_mov_b32_e32 v60, v228
	v_mov_b32_e32 v61, v229
	v_mov_b32_e32 v62, v230
	v_mov_b32_e32 v63, v231
	v_mov_b32_e32 v64, v232
	v_mov_b32_e32 v65, v233
	v_mov_b32_e32 v66, v234
	v_mov_b32_e32 v67, v235
	v_mov_b32_e32 v56, v224
	v_mov_b32_e32 v57, v225
	v_mov_b32_e32 v58, v226
	v_mov_b32_e32 v59, v227
	global_load_dwordx4 v[224:227], v[178:179], off offset:512
	global_load_dwordx4 v[228:231], v[140:141], off offset:512
	global_load_dwordx4 v[232:235], v[142:143], off offset:512
	v_sub_f32_e32 v57, v57, v76
	v_sub_f32_e32 v56, v56, v76
	v_sub_f32_e32 v59, v59, v76
	v_sub_f32_e32 v58, v58, v76
	v_pk_mul_f32 v[58:59], v[76:77], v[58:59] op_sel:[1,0]
	v_pk_mul_f32 v[56:57], v[76:77], v[56:57] op_sel:[1,0]
	v_pk_fma_f32 v[58:59], v[62:63], v[58:59], v[66:67]
	v_pk_fma_f32 v[56:57], v[60:61], v[56:57], v[64:65]
	v_pk_fma_f32 v[54:55], v[58:59], s[62:63], v[54:55] op_sel_hi:[1,0,1]
	v_pk_fma_f32 v[52:53], v[56:57], s[62:63], v[52:53] op_sel_hi:[1,0,1]
	global_store_dwordx4 v[78:79], v[52:55], off offset:512
	s_nop 0
	v_add_u32_e32 v64, 0x90, v146
	v_ashrrev_i32_e32 v65, 31, v64
	v_lshlrev_b32_e32 v66, 1, v64
	v_lshlrev_b64 v[64:65], 10, v[64:65]
	v_ashrrev_i32_e32 v67, 31, v66
	v_lshl_add_u64 v[64:65], v[64:65], 0, v[144:145]
	v_lshl_add_u64 v[66:67], v[66:67], 2, s[42:43]
	v_lshlrev_b64 v[64:65], 2, v[64:65]
	v_lshl_add_u64 v[68:69], s[0:1], 0, v[64:65]
	s_waitcnt vmcnt(14)
	v_mov_b32_e32 v56, v242
	v_mov_b32_e32 v57, v243
	v_mov_b32_e32 v58, v244
	v_mov_b32_e32 v59, v245
	v_mov_b32_e32 v60, v252
	v_mov_b32_e32 v61, v253
	v_mov_b32_e32 v62, v254
	v_mov_b32_e32 v63, v255
	v_mov_b32_e32 v52, v238
	v_mov_b32_e32 v53, v239
	v_mov_b32_e32 v54, v240
	v_mov_b32_e32 v55, v241
	global_load_dwordx4 v[238:241], v[178:179], off offset:576
	global_load_dwordx4 v[242:245], v[140:141], off offset:576
	global_load_dwordx4 v[252:255], v[142:143], off offset:576
	v_lshl_add_u64 v[178:179], v[178:179], 0, s[14:15]
	v_sub_f32_e32 v53, v53, v76
	v_sub_f32_e32 v52, v52, v76
	v_sub_f32_e32 v55, v55, v76
	v_sub_f32_e32 v54, v54, v76
	v_pk_mul_f32 v[54:55], v[76:77], v[54:55] op_sel:[1,0]
	v_pk_mul_f32 v[52:53], v[76:77], v[52:53] op_sel:[1,0]
	v_pk_fma_f32 v[54:55], v[58:59], v[54:55], v[62:63]
	v_pk_fma_f32 v[52:53], v[56:57], v[52:53], v[60:61]
	v_pk_fma_f32 v[50:51], v[54:55], s[62:63], v[50:51] op_sel_hi:[1,0,1]
	v_pk_fma_f32 v[48:49], v[52:53], s[62:63], v[48:49] op_sel_hi:[1,0,1]
	global_store_dwordx4 v[78:79], v[48:51], off offset:576
	v_lshl_add_u64 v[62:63], s[40:41], 0, v[64:65]
	s_waitcnt vmcnt(13)
	v_mov_b32_e32 v52, v190
	v_mov_b32_e32 v53, v191
	v_mov_b32_e32 v54, v192
	v_mov_b32_e32 v55, v193
	v_mov_b32_e32 v56, v194
	v_mov_b32_e32 v57, v195
	v_mov_b32_e32 v58, v196
	v_mov_b32_e32 v59, v197
	v_mov_b32_e32 v60, v198
	v_mov_b32_e32 v61, v199
	v_mov_b32_e32 v48, v186
	v_mov_b32_e32 v49, v187
	v_mov_b32_e32 v50, v188
	v_mov_b32_e32 v51, v189
	global_load_dwordx2 v[198:199], v[182:183], off offset:1280
	global_load_dwordx4 v[186:189], v[178:179], off
	global_load_dwordx4 v[190:193], v[140:141], off
	global_load_dwordx4 v[194:197], v[142:143], off
	v_sub_f32_e32 v49, v49, v60
	v_sub_f32_e32 v48, v48, v60
	v_sub_f32_e32 v51, v51, v60
	v_sub_f32_e32 v50, v50, v60
	v_pk_mul_f32 v[50:51], v[60:61], v[50:51] op_sel:[1,0]
	v_pk_mul_f32 v[48:49], v[60:61], v[48:49] op_sel:[1,0]
	v_pk_fma_f32 v[50:51], v[54:55], v[50:51], v[58:59]
	v_pk_fma_f32 v[48:49], v[52:53], v[48:49], v[56:57]
	v_pk_fma_f32 v[46:47], v[50:51], s[62:63], v[46:47] op_sel_hi:[1,0,1]
	v_pk_fma_f32 v[44:45], v[48:49], s[62:63], v[44:45] op_sel_hi:[1,0,1]
	global_store_dwordx4 v[62:63], v[44:47], off
	s_nop 0
	s_waitcnt vmcnt(14)
	v_mov_b32_e32 v48, v214
	v_mov_b32_e32 v49, v215
	v_mov_b32_e32 v50, v216
	v_mov_b32_e32 v51, v217
	v_mov_b32_e32 v52, v218
	v_mov_b32_e32 v53, v219
	v_mov_b32_e32 v54, v220
	v_mov_b32_e32 v55, v221
	v_mov_b32_e32 v44, v210
	v_mov_b32_e32 v45, v211
	v_mov_b32_e32 v46, v212
	v_mov_b32_e32 v47, v213
	global_load_dwordx4 v[210:213], v[178:179], off offset:64
	global_load_dwordx4 v[214:217], v[140:141], off offset:64
	global_load_dwordx4 v[218:221], v[142:143], off offset:64
	v_sub_f32_e32 v45, v45, v60
	v_sub_f32_e32 v44, v44, v60
	v_sub_f32_e32 v47, v47, v60
	v_sub_f32_e32 v46, v46, v60
	v_pk_mul_f32 v[46:47], v[60:61], v[46:47] op_sel:[1,0]
	v_pk_mul_f32 v[44:45], v[60:61], v[44:45] op_sel:[1,0]
	v_pk_fma_f32 v[46:47], v[50:51], v[46:47], v[54:55]
	v_pk_fma_f32 v[44:45], v[48:49], v[44:45], v[52:53]
	v_pk_fma_f32 v[42:43], v[46:47], s[62:63], v[42:43] op_sel_hi:[1,0,1]
	v_pk_fma_f32 v[40:41], v[44:45], s[62:63], v[40:41] op_sel_hi:[1,0,1]
	global_store_dwordx4 v[62:63], v[40:43], off offset:64
	s_nop 0
	s_waitcnt vmcnt(14)
	v_mov_b32_e32 v44, v228
	v_mov_b32_e32 v45, v229
	v_mov_b32_e32 v46, v230
	v_mov_b32_e32 v47, v231
	v_mov_b32_e32 v48, v232
	v_mov_b32_e32 v49, v233
	v_mov_b32_e32 v50, v234
	v_mov_b32_e32 v51, v235
	v_mov_b32_e32 v40, v224
	v_mov_b32_e32 v41, v225
	v_mov_b32_e32 v42, v226
	v_mov_b32_e32 v43, v227
	global_load_dwordx4 v[224:227], v[178:179], off offset:512
	global_load_dwordx4 v[228:231], v[140:141], off offset:512
	global_load_dwordx4 v[232:235], v[142:143], off offset:512
	v_sub_f32_e32 v41, v41, v60
	v_sub_f32_e32 v40, v40, v60
	v_sub_f32_e32 v43, v43, v60
	v_sub_f32_e32 v42, v42, v60
	v_pk_mul_f32 v[42:43], v[60:61], v[42:43] op_sel:[1,0]
	v_pk_mul_f32 v[40:41], v[60:61], v[40:41] op_sel:[1,0]
	v_pk_fma_f32 v[42:43], v[46:47], v[42:43], v[50:51]
	v_pk_fma_f32 v[40:41], v[44:45], v[40:41], v[48:49]
	v_pk_fma_f32 v[38:39], v[42:43], s[62:63], v[38:39] op_sel_hi:[1,0,1]
	v_pk_fma_f32 v[36:37], v[40:41], s[62:63], v[36:37] op_sel_hi:[1,0,1]
	global_store_dwordx4 v[62:63], v[36:39], off offset:512
	s_nop 0
	v_add_u32_e32 v48, 0xa0, v146
	v_ashrrev_i32_e32 v49, 31, v48
	v_lshlrev_b32_e32 v50, 1, v48
	v_lshlrev_b64 v[48:49], 10, v[48:49]
	v_ashrrev_i32_e32 v51, 31, v50
	v_lshl_add_u64 v[48:49], v[48:49], 0, v[144:145]
	v_lshl_add_u64 v[50:51], v[50:51], 2, s[42:43]
	v_lshlrev_b64 v[48:49], 2, v[48:49]
	v_lshl_add_u64 v[52:53], s[0:1], 0, v[48:49]
	s_waitcnt vmcnt(14)
;     __device__ __forceinline__ void operator()(const f32x4 (&acc)[2][2][4][2], const Unit& u, int wr, int wc, int fr, int fq) const {
;         const int row0 = u.pm * BM + wr * 64 + fr, col0 = u.pn * BM + wc * 32 + 4 * fq;
; #pragma unroll
;         for (int ai = 0; ai < 2; ++ai)
; #pragma unroll
;             for (int m = 0; m < 4; ++m) { const int r = row0 + ai * HALF + m * 16; const size_t off = (size_t)r * DM + col0;
;                 const float mu = stat[2 * r], rs = stat[2 * r + 1];
; #pragma unroll
;                 for (int bj = 0; bj < 2; ++bj)
; #pragma unroll
;                     for (int n = 0; n < 2; ++n) { const int c = bj * HALF + n * 16; const f32x4 y = *(const f32x4*)(Yin + off + c);
;                         const f32x4 gg = *(const f32x4*)(g + col0 + c), bb = *(const f32x4*)(b + col0 + c);
;                         const f32x4 x = (y - mu) * rs * gg + bb;
;                         *(f32x4*)(Yout + off + c) = x * ALPHA + acc[ai][bj][m][n]; }
;                 asm volatile("" ::: "memory"); }
	v_mov_b32_e32 v40, v242
	v_mov_b32_e32 v41, v243
	v_mov_b32_e32 v42, v244
	v_mov_b32_e32 v43, v245
	v_mov_b32_e32 v44, v252
	v_mov_b32_e32 v45, v253
	v_mov_b32_e32 v46, v254
	v_mov_b32_e32 v47, v255
	v_mov_b32_e32 v36, v238
	v_mov_b32_e32 v37, v239
	v_mov_b32_e32 v38, v240
	v_mov_b32_e32 v39, v241
	global_load_dwordx4 v[238:241], v[178:179], off offset:576
	global_load_dwordx4 v[242:245], v[140:141], off offset:576
	global_load_dwordx4 v[252:255], v[142:143], off offset:576
	v_lshl_add_u64 v[178:179], v[178:179], 0, s[14:15]
	v_sub_f32_e32 v37, v37, v60
	v_sub_f32_e32 v36, v36, v60
	v_sub_f32_e32 v39, v39, v60
	v_sub_f32_e32 v38, v38, v60
	v_pk_mul_f32 v[38:39], v[60:61], v[38:39] op_sel:[1,0]
	v_pk_mul_f32 v[36:37], v[60:61], v[36:37] op_sel:[1,0]
	v_pk_fma_f32 v[38:39], v[42:43], v[38:39], v[46:47]
	v_pk_fma_f32 v[36:37], v[40:41], v[36:37], v[44:45]
	v_pk_fma_f32 v[34:35], v[38:39], s[62:63], v[34:35] op_sel_hi:[1,0,1]
	v_pk_fma_f32 v[32:33], v[36:37], s[62:63], v[32:33] op_sel_hi:[1,0,1]
	global_store_dwordx4 v[62:63], v[32:35], off offset:576
	v_lshl_add_u64 v[46:47], s[40:41], 0, v[48:49]
	s_waitcnt vmcnt(13)
	v_mov_b32_e32 v36, v190
	v_mov_b32_e32 v37, v191
	v_mov_b32_e32 v38, v192
	v_mov_b32_e32 v39, v193
	v_mov_b32_e32 v40, v194
	v_mov_b32_e32 v41, v195
	v_mov_b32_e32 v42, v196
	v_mov_b32_e32 v43, v197
	v_mov_b32_e32 v44, v198
	v_mov_b32_e32 v45, v199
	v_mov_b32_e32 v32, v186
	v_mov_b32_e32 v33, v187
	v_mov_b32_e32 v34, v188
	v_mov_b32_e32 v35, v189
	global_load_dwordx2 v[198:199], v[182:183], off offset:1408
	global_load_dwordx4 v[186:189], v[178:179], off
	global_load_dwordx4 v[190:193], v[140:141], off
	global_load_dwordx4 v[194:197], v[142:143], off
	v_sub_f32_e32 v33, v33, v44
	v_sub_f32_e32 v32, v32, v44
	v_sub_f32_e32 v35, v35, v44
	v_sub_f32_e32 v34, v34, v44
	v_pk_mul_f32 v[34:35], v[44:45], v[34:35] op_sel:[1,0]
	v_pk_mul_f32 v[32:33], v[44:45], v[32:33] op_sel:[1,0]
	v_pk_fma_f32 v[34:35], v[38:39], v[34:35], v[42:43]
	v_pk_fma_f32 v[32:33], v[36:37], v[32:33], v[40:41]
	v_pk_fma_f32 v[30:31], v[34:35], s[62:63], v[30:31] op_sel_hi:[1,0,1]
	v_pk_fma_f32 v[28:29], v[32:33], s[62:63], v[28:29] op_sel_hi:[1,0,1]
	global_store_dwordx4 v[46:47], v[28:31], off
	s_nop 0
	s_waitcnt vmcnt(14)
	v_mov_b32_e32 v32, v214
	v_mov_b32_e32 v33, v215
	v_mov_b32_e32 v34, v216
	v_mov_b32_e32 v35, v217
	v_mov_b32_e32 v36, v218
	v_mov_b32_e32 v37, v219
	v_mov_b32_e32 v38, v220
	v_mov_b32_e32 v39, v221
	v_mov_b32_e32 v28, v210
	v_mov_b32_e32 v29, v211
	v_mov_b32_e32 v30, v212
	v_mov_b32_e32 v31, v213
	global_load_dwordx4 v[210:213], v[178:179], off offset:64
	global_load_dwordx4 v[214:217], v[140:141], off offset:64
	global_load_dwordx4 v[218:221], v[142:143], off offset:64
	v_sub_f32_e32 v29, v29, v44
	v_sub_f32_e32 v28, v28, v44
	v_sub_f32_e32 v31, v31, v44
	v_sub_f32_e32 v30, v30, v44
	v_pk_mul_f32 v[30:31], v[44:45], v[30:31] op_sel:[1,0]
	v_pk_mul_f32 v[28:29], v[44:45], v[28:29] op_sel:[1,0]
	v_pk_fma_f32 v[30:31], v[34:35], v[30:31], v[38:39]
	v_pk_fma_f32 v[28:29], v[32:33], v[28:29], v[36:37]
	v_pk_fma_f32 v[26:27], v[30:31], s[62:63], v[26:27] op_sel_hi:[1,0,1]
	v_pk_fma_f32 v[24:25], v[28:29], s[62:63], v[24:25] op_sel_hi:[1,0,1]
	global_store_dwordx4 v[46:47], v[24:27], off offset:64
	s_nop 0
	s_waitcnt vmcnt(14)
	v_mov_b32_e32 v28, v228
	v_mov_b32_e32 v29, v229
	v_mov_b32_e32 v30, v230
	v_mov_b32_e32 v31, v231
	v_mov_b32_e32 v32, v232
	v_mov_b32_e32 v33, v233
	v_mov_b32_e32 v34, v234
	v_mov_b32_e32 v35, v235
	v_mov_b32_e32 v24, v224
	v_mov_b32_e32 v25, v225
	v_mov_b32_e32 v26, v226
	v_mov_b32_e32 v27, v227
	global_load_dwordx4 v[224:227], v[178:179], off offset:512
	global_load_dwordx4 v[228:231], v[140:141], off offset:512
	global_load_dwordx4 v[232:235], v[142:143], off offset:512
	v_sub_f32_e32 v25, v25, v44
	v_sub_f32_e32 v24, v24, v44
	v_sub_f32_e32 v27, v27, v44
	v_sub_f32_e32 v26, v26, v44
	v_pk_mul_f32 v[26:27], v[44:45], v[26:27] op_sel:[1,0]
	v_pk_mul_f32 v[24:25], v[44:45], v[24:25] op_sel:[1,0]
	v_pk_fma_f32 v[26:27], v[30:31], v[26:27], v[34:35]
	v_pk_fma_f32 v[24:25], v[28:29], v[24:25], v[32:33]
	v_pk_fma_f32 v[22:23], v[26:27], s[62:63], v[22:23] op_sel_hi:[1,0,1]
	v_pk_fma_f32 v[20:21], v[24:25], s[62:63], v[20:21] op_sel_hi:[1,0,1]
	global_store_dwordx4 v[46:47], v[20:23], off offset:512
	s_nop 0
	v_add_u32_e32 v32, 0xb0, v146
	v_ashrrev_i32_e32 v33, 31, v32
	v_lshlrev_b32_e32 v34, 1, v32
	v_lshlrev_b64 v[32:33], 10, v[32:33]
	v_ashrrev_i32_e32 v35, 31, v34
	v_lshl_add_u64 v[32:33], v[32:33], 0, v[144:145]
	v_lshl_add_u64 v[34:35], v[34:35], 2, s[42:43]
	v_lshlrev_b64 v[32:33], 2, v[32:33]
	v_lshl_add_u64 v[36:37], s[0:1], 0, v[32:33]
	s_waitcnt vmcnt(14)
;     __device__ __forceinline__ void operator()(const f32x4 (&acc)[2][2][4][2], const Unit& u, int wr, int wc, int fr, int fq) const {
;         const int row0 = u.pm * BM + wr * 64 + fr, col0 = u.pn * BM + wc * 32 + 4 * fq;
; #pragma unroll
;         for (int ai = 0; ai < 2; ++ai)
; #pragma unroll
;             for (int m = 0; m < 4; ++m) { const int r = row0 + ai * HALF + m * 16; const size_t off = (size_t)r * DM + col0;
;                 const float mu = stat[2 * r], rs = stat[2 * r + 1];
; #pragma unroll
;                 for (int bj = 0; bj < 2; ++bj)
; #pragma unroll
;                     for (int n = 0; n < 2; ++n) { const int c = bj * HALF + n * 16; const f32x4 y = *(const f32x4*)(Yin + off + c);
;                         const f32x4 gg = *(const f32x4*)(g + col0 + c), bb = *(const f32x4*)(b + col0 + c);
;                         const f32x4 x = (y - mu) * rs * gg + bb;
;                         *(f32x4*)(Yout + off + c) = x * ALPHA + acc[ai][bj][m][n]; }
;                 asm volatile("" ::: "memory"); }
	v_mov_b32_e32 v24, v242
	v_mov_b32_e32 v25, v243
	v_mov_b32_e32 v26, v244
	v_mov_b32_e32 v27, v245
	v_mov_b32_e32 v28, v252
	v_mov_b32_e32 v29, v253
	v_mov_b32_e32 v30, v254
	v_mov_b32_e32 v31, v255
	v_mov_b32_e32 v20, v238
	v_mov_b32_e32 v21, v239
	v_mov_b32_e32 v22, v240
	v_mov_b32_e32 v23, v241
	global_load_dwordx4 v[238:241], v[178:179], off offset:576
	global_load_dwordx4 v[242:245], v[140:141], off offset:576
	global_load_dwordx4 v[252:255], v[142:143], off offset:576
	v_sub_f32_e32 v21, v21, v44
	v_sub_f32_e32 v20, v20, v44
	v_sub_f32_e32 v23, v23, v44
	v_sub_f32_e32 v22, v22, v44
	v_pk_mul_f32 v[22:23], v[44:45], v[22:23] op_sel:[1,0]
	v_pk_mul_f32 v[20:21], v[44:45], v[20:21] op_sel:[1,0]
	v_pk_fma_f32 v[22:23], v[26:27], v[22:23], v[30:31]
	v_pk_fma_f32 v[20:21], v[24:25], v[20:21], v[28:29]
	v_pk_fma_f32 v[18:19], v[22:23], s[62:63], v[18:19] op_sel_hi:[1,0,1]
	v_pk_fma_f32 v[16:17], v[20:21], s[62:63], v[16:17] op_sel_hi:[1,0,1]
	global_store_dwordx4 v[46:47], v[16:19], off offset:576
	v_lshl_add_u64 v[30:31], s[40:41], 0, v[32:33]
	s_waitcnt vmcnt(13)
	v_mov_b32_e32 v20, v190
	v_mov_b32_e32 v21, v191
	v_mov_b32_e32 v22, v192
	v_mov_b32_e32 v23, v193
	v_mov_b32_e32 v24, v194
	v_mov_b32_e32 v25, v195
	v_mov_b32_e32 v26, v196
	v_mov_b32_e32 v27, v197
	v_mov_b32_e32 v28, v198
	v_mov_b32_e32 v29, v199
	v_mov_b32_e32 v16, v186
	v_mov_b32_e32 v17, v187
	v_mov_b32_e32 v18, v188
	v_mov_b32_e32 v19, v189
	v_sub_f32_e32 v17, v17, v28
	v_sub_f32_e32 v16, v16, v28
	v_sub_f32_e32 v19, v19, v28
	v_sub_f32_e32 v18, v18, v28
	v_pk_mul_f32 v[18:19], v[28:29], v[18:19] op_sel:[1,0]
	v_pk_mul_f32 v[16:17], v[28:29], v[16:17] op_sel:[1,0]
	v_pk_fma_f32 v[18:19], v[22:23], v[18:19], v[26:27]
	v_pk_fma_f32 v[16:17], v[20:21], v[16:17], v[24:25]
	v_pk_fma_f32 v[14:15], v[18:19], s[62:63], v[14:15] op_sel_hi:[1,0,1]
	v_pk_fma_f32 v[12:13], v[16:17], s[62:63], v[12:13] op_sel_hi:[1,0,1]
	global_store_dwordx4 v[30:31], v[12:15], off
	s_nop 0
	s_waitcnt vmcnt(10)
	v_mov_b32_e32 v16, v214
	v_mov_b32_e32 v17, v215
	v_mov_b32_e32 v18, v216
	v_mov_b32_e32 v19, v217
	v_mov_b32_e32 v20, v218
	v_mov_b32_e32 v21, v219
	v_mov_b32_e32 v22, v220
	v_mov_b32_e32 v23, v221
	v_mov_b32_e32 v12, v210
	v_mov_b32_e32 v13, v211
	v_mov_b32_e32 v14, v212
	v_mov_b32_e32 v15, v213
	v_sub_f32_e32 v13, v13, v28
	v_sub_f32_e32 v12, v12, v28
	v_sub_f32_e32 v15, v15, v28
	v_sub_f32_e32 v14, v14, v28
	v_pk_mul_f32 v[14:15], v[28:29], v[14:15] op_sel:[1,0]
	v_pk_mul_f32 v[12:13], v[28:29], v[12:13] op_sel:[1,0]
	v_pk_fma_f32 v[14:15], v[18:19], v[14:15], v[22:23]
	v_pk_fma_f32 v[12:13], v[16:17], v[12:13], v[20:21]
	v_pk_fma_f32 v[10:11], v[14:15], s[62:63], v[10:11] op_sel_hi:[1,0,1]
	v_pk_fma_f32 v[8:9], v[12:13], s[62:63], v[8:9] op_sel_hi:[1,0,1]
	global_store_dwordx4 v[30:31], v[8:11], off offset:64
	s_nop 0
	s_waitcnt vmcnt(7)
	v_mov_b32_e32 v12, v228
	v_mov_b32_e32 v13, v229
	v_mov_b32_e32 v14, v230
	v_mov_b32_e32 v15, v231
	v_mov_b32_e32 v16, v232
	v_mov_b32_e32 v17, v233
	v_mov_b32_e32 v18, v234
	v_mov_b32_e32 v19, v235
	v_mov_b32_e32 v8, v224
	v_mov_b32_e32 v9, v225
	v_mov_b32_e32 v10, v226
	v_mov_b32_e32 v11, v227
	v_sub_f32_e32 v9, v9, v28
	v_sub_f32_e32 v8, v8, v28
	v_sub_f32_e32 v11, v11, v28
	v_sub_f32_e32 v10, v10, v28
	v_pk_mul_f32 v[10:11], v[28:29], v[10:11] op_sel:[1,0]
	v_pk_mul_f32 v[8:9], v[28:29], v[8:9] op_sel:[1,0]
	v_pk_fma_f32 v[10:11], v[14:15], v[10:11], v[18:19]
	v_pk_fma_f32 v[8:9], v[12:13], v[8:9], v[16:17]
	v_pk_fma_f32 v[6:7], v[10:11], s[62:63], v[6:7] op_sel_hi:[1,0,1]
	v_pk_fma_f32 v[4:5], v[8:9], s[62:63], v[4:5] op_sel_hi:[1,0,1]
	global_store_dwordx4 v[30:31], v[4:7], off offset:512
	s_nop 0
	s_waitcnt vmcnt(4)
	v_mov_b32_e32 v8, v242
	v_mov_b32_e32 v9, v243
	v_mov_b32_e32 v10, v244
	v_mov_b32_e32 v11, v245
	v_mov_b32_e32 v12, v252
	v_mov_b32_e32 v13, v253
	v_mov_b32_e32 v14, v254
	v_mov_b32_e32 v15, v255
	v_mov_b32_e32 v4, v238
	v_mov_b32_e32 v5, v239
	v_mov_b32_e32 v6, v240
	v_mov_b32_e32 v7, v241
	v_sub_f32_e32 v5, v5, v28
	v_sub_f32_e32 v4, v4, v28
	v_sub_f32_e32 v7, v7, v28
	v_sub_f32_e32 v6, v6, v28
	v_pk_mul_f32 v[6:7], v[28:29], v[6:7] op_sel:[1,0]
	v_pk_mul_f32 v[4:5], v[28:29], v[4:5] op_sel:[1,0]
	v_pk_fma_f32 v[6:7], v[10:11], v[6:7], v[14:15]
	v_pk_fma_f32 v[4:5], v[8:9], v[4:5], v[12:13]
	v_pk_fma_f32 v[2:3], v[6:7], s[62:63], v[2:3] op_sel_hi:[1,0,1]
	v_pk_fma_f32 v[0:1], v[4:5], s[62:63], v[0:1] op_sel_hi:[1,0,1]
	global_store_dwordx4 v[30:31], v[0:3], off offset:576
	s_cbranch_vccnz .LBB0_793
	s_andn2_b64 vcc, exec, s[34:35]
	s_cbranch_vccnz .LBB0_792
	s_barrier
	s_branch .LBB0_792

; __global__ void __launch_bounds__(NWAVES * 64, 2) mega_fwd(Args args) {
	.amdhsa_kernel _Z8mega_fwd4Args
		.amdhsa_group_segment_fixed_size 0
		.amdhsa_private_segment_fixed_size 0
		.amdhsa_kernarg_size 448
		.amdhsa_user_sgpr_count 2
		.amdhsa_user_sgpr_dispatch_ptr 0
		.amdhsa_user_sgpr_queue_ptr 0
		.amdhsa_user_sgpr_kernarg_segment_ptr 1
		.amdhsa_user_sgpr_dispatch_id 0
		.amdhsa_user_sgpr_kernarg_preload_length 0
		.amdhsa_user_sgpr_kernarg_preload_offset 0
		.amdhsa_user_sgpr_private_segment_size 0
		.amdhsa_uses_dynamic_stack 0
		.amdhsa_enable_private_segment 0
		.amdhsa_system_sgpr_workgroup_id_x 1
		.amdhsa_system_sgpr_workgroup_id_y 0
		.amdhsa_system_sgpr_workgroup_id_z 0
		.amdhsa_system_sgpr_workgroup_info 0
		.amdhsa_system_vgpr_workitem_id 2
		.amdhsa_next_free_vgpr 256
		.amdhsa_next_free_sgpr 98
		.amdhsa_accum_offset 256
		.amdhsa_reserve_vcc 1
		.amdhsa_float_round_mode_32 0
		.amdhsa_float_round_mode_16_64 0
		.amdhsa_float_denorm_mode_32 3
		.amdhsa_float_denorm_mode_16_64 3
		.amdhsa_dx10_clamp 1
		.amdhsa_ieee_mode 1
		.amdhsa_fp16_overflow 0
		.amdhsa_tg_split 0
		.amdhsa_exception_fp_ieee_invalid_op 0
		.amdhsa_exception_fp_denorm_src 0
		.amdhsa_exception_fp_ieee_div_zero 0
		.amdhsa_exception_fp_ieee_overflow 0
		.amdhsa_exception_fp_ieee_underflow 0
		.amdhsa_exception_fp_ieee_inexact 0
		.amdhsa_exception_int_div_zero 0
	.end_amdhsa_kernel

; __global__ void __launch_bounds__(NWAVES * 64, 2) mega_fwd(Args args) {
amdhsa.kernels:
  - .agpr_count:     0
    .args:
      - .offset:         0
        .size:           192
        .value_kind:     by_value
      - .offset:         192
        .size:           4
        .value_kind:     hidden_block_count_x
      - .offset:         196
        .size:           4
        .value_kind:     hidden_block_count_y
      - .offset:         200
        .size:           4
        .value_kind:     hidden_block_count_z
      - .offset:         204
        .size:           2
        .value_kind:     hidden_group_size_x
      - .offset:         206
        .size:           2
        .value_kind:     hidden_group_size_y
      - .offset:         208
        .size:           2
        .value_kind:     hidden_group_size_z
      - .offset:         210
        .size:           2
        .value_kind:     hidden_remainder_x
      - .offset:         212
        .size:           2
        .value_kind:     hidden_remainder_y
      - .offset:         214
        .size:           2
        .value_kind:     hidden_remainder_z
      - .offset:         232
        .size:           8
        .value_kind:     hidden_global_offset_x
      - .offset:         240
        .size:           8
        .value_kind:     hidden_global_offset_y
      - .offset:         248
        .size:           8
        .value_kind:     hidden_global_offset_z
      - .offset:         256
        .size:           2
        .value_kind:     hidden_grid_dims
      - .offset:         280
        .size:           8
        .value_kind:     hidden_multigrid_sync_arg
      - .offset:         312
        .size:           4
        .value_kind:     hidden_dynamic_lds_size
    .group_segment_fixed_size: 0
    .kernarg_segment_align: 8
    .kernarg_segment_size: 448
    .language:       OpenCL C
    .language_version:
      - 2
      - 0
    .max_flat_workgroup_size: 512
    .name:           _Z8mega_fwd4Args
    .private_segment_fixed_size: 0
    .sgpr_count:     104
    .sgpr_spill_count: 219
    .symbol:         _Z8mega_fwd4Args.kd
    .uniform_work_group_size: 1
    .uses_dynamic_stack: false
    .vgpr_count:     256
    .vgpr_spill_count: 0
    .wavefront_size: 64
